# combo, phase-C balance k=2
# speedup vs baseline: 1.0080x; 1.0073x over previous
; __global__ void __launch_bounds__(256, 2) hybrid_megakernel(Params p) {
;     ...
;       int start = 0, mine = 0;
;       for (int g2 = 0; g2 <= gi; ++g2) {
;         const int n = 32 - g2;
;         const int d = (n <= 10) ? 2 : (n <= 22) ? 1 : 0;
;         if (g2 < gi) start += 2 * d; else mine = d;
;       }
;       start += ((vb >> 3) & 1) * mine;
.LBB0_407:
	s_cmp_gt_u32 s2, 1
	s_cselect_b64 s[4:5], -1, 0
	s_cmp_lt_u32 s2, 30
	v_cndmask_b32_e64 v1, 0, 1, s[4:5]
	s_cselect_b64 vcc, -1, 0
	v_cndmask_b32_e32 v1, 2, v1, vcc
	s_cmp_lt_i32 s2, s0
	v_lshlrev_b32_e32 v2, 1, v1
	s_cselect_b64 vcc, -1, 0
	s_add_i32 s2, s2, 1
	v_cndmask_b32_e32 v2, 0, v2, vcc
	v_cndmask_b32_e32 v116, v1, v116, vcc
	s_cmp_eq_u32 s1, s2
	v_add_u32_e32 v0, v2, v0
	s_cbranch_scc0 .LBB0_407
	v_cmp_gt_i32_e32 vcc, 1, v116
	s_cbranch_vccz .LBB0_410
	s_branch .LBB0_345
